# combined: relaxed first-iteration stage waits + MFMA-section entry cleanup + jumped-over alignment padding + faster gate polling
# baseline (speedup 1.0000x reference)
.LBB0_287:
	s_ashr_i32 s21, s20, 31
	s_lshl_b64 s[22:23], s[20:21], 19
	s_add_u32 s22, s80, s22
	s_addc_u32 s23, s81, s23
	s_and_b64 s[24:25], s[6:7], exec
	s_cselect_b32 s21, s23, s29
	s_cselect_b32 s36, s22, s28
	s_ashr_i32 s19, s18, 31
	s_lshl_b64 s[24:25], s[18:19], 19
	s_add_u32 s24, s40, s24
	s_addc_u32 s25, s41, s25
	s_and_b64 s[34:35], s[6:7], exec
	s_cselect_b32 s19, s25, s31
	s_cselect_b32 s37, s24, s30
	s_add_u32 s38, s30, 0x100
	s_addc_u32 s39, s31, 0
	s_add_u32 s28, s28, 0x40080
	s_addc_u32 s29, s29, 0
	s_mov_b32 s55, -2
	s_add_u32 s30, s28, 0xfffc0080
	s_addc_u32 s31, s29, -1
	s_add_i32 s56, 0, 0x10000
	s_cmp_eq_u32 s55, 12
	s_cselect_b32 s35, s21, s31
	s_cselect_b32 s34, s36, s30
	s_cselect_b32 s31, s19, s39
	s_cselect_b32 s30, s37, s38
	s_add_i32 s58, 0, 0x14000
	v_add_u32_e32 v166, s56, v147
	v_add_u32_e32 v182, s58, v147
	ds_read_b128 v[142:145], v166
	ds_read_b128 v[158:161], v166 offset:1024
	ds_read_b128 v[162:165], v166 offset:2048
	ds_read_b128 v[166:169], v166 offset:3072
	ds_read_b128 v[170:173], v182
	ds_read_b128 v[174:177], v182 offset:1024
	ds_read_b128 v[178:181], v182 offset:2048
	ds_read_b128 v[182:185], v182 offset:3072
	v_lshl_add_u64 v[224:225], s[28:29], 0, v[140:141]
	s_add_i32 m0, s44, 0xc000
	ds_read_b128 v[186:189], v157
	ds_read_b128 v[190:193], v157 offset:1024
	ds_read_b128 v[194:197], v157 offset:2048
	ds_read_b128 v[198:201], v157 offset:3072
	ds_read_b128 v[202:205], v157 offset:4096
	ds_read_b128 v[206:209], v157 offset:5120
	ds_read_b128 v[220:223], v157 offset:6144
	ds_read_b128 v[236:239], v157 offset:7168
	global_load_lds_dwordx4 v[224:225], off
	s_add_i32 m0, s44, 0xe000
	v_lshl_add_u64 v[224:225], s[28:29], 0, v[138:139]
	global_load_lds_dwordx4 v[224:225], off
	s_nop 0
	s_nop 0
	s_nop 0
	s_nop 0
	s_nop 0
	s_nop 0
	s_nop 0
	s_nop 0
	s_nop 0
	s_nop 0
	s_nop 0
	s_nop 0
	s_nop 0
	s_nop 0
	s_nop 0
	s_nop 0
	s_nop 0
	s_nop 0
	s_cmp_eq_u32 s9, 0
	s_cbranch_scc1 .Lkq_fw0
	s_waitcnt vmcnt(24)
	s_branch .Lkq_fj0

.Lkq_fj0:
	s_waitcnt lgkmcnt(0)
	s_barrier
	v_mfma_f32_16x16x32_bf16 v[126:129], v[142:145], v[186:189], 0
	v_mfma_f32_16x16x32_bf16 v[122:125], v[162:165], v[186:189], 0
	v_mfma_f32_16x16x32_bf16 v[110:113], v[142:145], v[194:197], 0
	v_mfma_f32_16x16x32_bf16 v[106:109], v[162:165], v[194:197], 0
	v_mfma_f32_16x16x32_bf16 v[94:97], v[142:145], v[202:205], 0
	v_mfma_f32_16x16x32_bf16 v[90:93], v[162:165], v[202:205], 0
	v_mfma_f32_16x16x32_bf16 v[78:81], v[142:145], v[220:223], 0
	v_mfma_f32_16x16x32_bf16 v[74:77], v[162:165], v[220:223], 0
	v_mfma_f32_16x16x32_bf16 v[126:129], v[158:161], v[190:193], v[126:129]
	v_mfma_f32_16x16x32_bf16 v[122:125], v[166:169], v[190:193], v[122:125]
	v_mfma_f32_16x16x32_bf16 v[110:113], v[158:161], v[198:201], v[110:113]
	v_mfma_f32_16x16x32_bf16 v[106:109], v[166:169], v[198:201], v[106:109]
	v_mfma_f32_16x16x32_bf16 v[94:97], v[158:161], v[206:209], v[94:97]
	v_mfma_f32_16x16x32_bf16 v[90:93], v[166:169], v[206:209], v[90:93]
	v_mfma_f32_16x16x32_bf16 v[78:81], v[158:161], v[236:239], v[78:81]
	v_mfma_f32_16x16x32_bf16 v[74:77], v[166:169], v[236:239], v[74:77]
	v_mfma_f32_16x16x32_bf16 v[118:121], v[170:173], v[186:189], 0
	v_mfma_f32_16x16x32_bf16 v[114:117], v[178:181], v[186:189], 0
	v_mfma_f32_16x16x32_bf16 v[102:105], v[170:173], v[194:197], 0
	v_mfma_f32_16x16x32_bf16 v[98:101], v[178:181], v[194:197], 0
	v_mfma_f32_16x16x32_bf16 v[86:89], v[170:173], v[202:205], 0
	v_mfma_f32_16x16x32_bf16 v[82:85], v[178:181], v[202:205], 0
	v_mfma_f32_16x16x32_bf16 v[70:73], v[170:173], v[220:223], 0
	v_mfma_f32_16x16x32_bf16 v[66:69], v[178:181], v[220:223], 0
	v_mfma_f32_16x16x32_bf16 v[118:121], v[174:177], v[190:193], v[118:121]
	v_mfma_f32_16x16x32_bf16 v[114:117], v[182:185], v[190:193], v[114:117]
	v_mfma_f32_16x16x32_bf16 v[102:105], v[174:177], v[198:201], v[102:105]
	v_mfma_f32_16x16x32_bf16 v[98:101], v[182:185], v[198:201], v[98:101]
	v_mfma_f32_16x16x32_bf16 v[86:89], v[174:177], v[206:209], v[86:89]
	v_mfma_f32_16x16x32_bf16 v[82:85], v[182:185], v[206:209], v[82:85]
	v_mfma_f32_16x16x32_bf16 v[70:73], v[174:177], v[236:239], v[70:73]
	v_mfma_f32_16x16x32_bf16 v[66:69], v[182:185], v[236:239], v[66:69]
	s_barrier
	s_add_i32 s56, s56, s27
	v_lshl_add_u64 v[224:225], s[30:31], 0, v[132:133]
	s_mov_b32 m0, s56
	ds_read_b128 v[186:189], v157 offset:16384
	ds_read_b128 v[190:193], v157 offset:17408
	ds_read_b128 v[194:197], v157 offset:18432
	ds_read_b128 v[198:201], v157 offset:19456
	ds_read_b128 v[202:205], v157 offset:20480
	ds_read_b128 v[206:209], v157 offset:21504
	ds_read_b128 v[220:223], v157 offset:22528
	ds_read_b128 v[236:239], v157 offset:23552
	global_load_lds_dwordx4 v[224:225], off
	s_add_i32 m0, s56, 0x2000
	s_add_u32 s56, s30, 0x40000
	v_lshl_add_u64 v[230:231], s[30:31], 0, v[136:137]
	s_addc_u32 s57, s31, 0
	s_add_i32 s58, s58, s27
	global_load_lds_dwordx4 v[230:231], off
	v_lshl_add_u64 v[240:241], s[56:57], 0, v[132:133]
	s_mov_b32 m0, s58
	v_lshl_add_u64 v[242:243], s[34:35], 0, v[134:135]
	global_load_lds_dwordx4 v[240:241], off
	s_add_i32 m0, s58, 0x2000
	v_lshl_add_u64 v[240:241], s[56:57], 0, v[136:137]
	global_load_lds_dwordx4 v[240:241], off
	s_mov_b32 m0, s44
	v_lshl_add_u64 v[240:241], s[34:35], 0, v[130:131]
	global_load_lds_dwordx4 v[240:241], off
	s_mov_b32 m0, s45
	s_nop 0
	global_load_lds_dwordx4 v[242:243], off
	s_nop 0
	s_nop 0
	s_nop 0
	s_nop 0
	s_nop 0
	s_nop 0
	s_nop 0
	s_nop 0
	s_nop 0
	s_nop 0
	s_nop 0
	s_nop 0
	s_nop 0
	s_nop 0
	s_nop 0
	s_nop 0
	s_nop 0
	s_nop 0
	s_cmp_eq_u32 s9, 0
	s_cbranch_scc1 .Lkq_fw1
	s_waitcnt vmcnt(24)
	s_branch .Lkq_fj1

.Lkq_fj1:
	s_waitcnt lgkmcnt(0)
	s_barrier
	v_mfma_f32_16x16x32_bf16 v[62:65], v[142:145], v[186:189], 0
	v_mfma_f32_16x16x32_bf16 v[58:61], v[162:165], v[186:189], 0
	v_mfma_f32_16x16x32_bf16 v[46:49], v[142:145], v[194:197], 0
	v_mfma_f32_16x16x32_bf16 v[42:45], v[162:165], v[194:197], 0
	v_mfma_f32_16x16x32_bf16 v[30:33], v[142:145], v[202:205], 0
	v_mfma_f32_16x16x32_bf16 v[26:29], v[162:165], v[202:205], 0
	v_mfma_f32_16x16x32_bf16 v[14:17], v[142:145], v[220:223], 0
	v_mfma_f32_16x16x32_bf16 v[10:13], v[162:165], v[220:223], 0
	v_mfma_f32_16x16x32_bf16 v[62:65], v[158:161], v[190:193], v[62:65]
	v_mfma_f32_16x16x32_bf16 v[58:61], v[166:169], v[190:193], v[58:61]
	v_mfma_f32_16x16x32_bf16 v[46:49], v[158:161], v[198:201], v[46:49]
	v_mfma_f32_16x16x32_bf16 v[42:45], v[166:169], v[198:201], v[42:45]
	v_mfma_f32_16x16x32_bf16 v[30:33], v[158:161], v[206:209], v[30:33]
	v_mfma_f32_16x16x32_bf16 v[26:29], v[166:169], v[206:209], v[26:29]
	v_mfma_f32_16x16x32_bf16 v[14:17], v[158:161], v[236:239], v[14:17]
	v_mfma_f32_16x16x32_bf16 v[10:13], v[166:169], v[236:239], v[10:13]
	v_mfma_f32_16x16x32_bf16 v[54:57], v[170:173], v[186:189], 0
	v_mfma_f32_16x16x32_bf16 v[50:53], v[178:181], v[186:189], 0
	v_mfma_f32_16x16x32_bf16 v[38:41], v[170:173], v[194:197], 0
	v_mfma_f32_16x16x32_bf16 v[34:37], v[178:181], v[194:197], 0
	v_mfma_f32_16x16x32_bf16 v[22:25], v[170:173], v[202:205], 0
	v_mfma_f32_16x16x32_bf16 v[18:21], v[178:181], v[202:205], 0
	v_mfma_f32_16x16x32_bf16 v[6:9], v[170:173], v[220:223], 0
	v_mfma_f32_16x16x32_bf16 v[2:5], v[178:181], v[220:223], 0
	v_mfma_f32_16x16x32_bf16 v[54:57], v[174:177], v[190:193], v[54:57]
	v_mfma_f32_16x16x32_bf16 v[50:53], v[182:185], v[190:193], v[50:53]
	v_mfma_f32_16x16x32_bf16 v[38:41], v[174:177], v[198:201], v[38:41]
	v_mfma_f32_16x16x32_bf16 v[34:37], v[182:185], v[198:201], v[34:37]
	v_mfma_f32_16x16x32_bf16 v[22:25], v[174:177], v[206:209], v[22:25]
	v_mfma_f32_16x16x32_bf16 v[18:21], v[182:185], v[206:209], v[18:21]
	v_mfma_f32_16x16x32_bf16 v[6:9], v[174:177], v[236:239], v[6:9]
	v_mfma_f32_16x16x32_bf16 v[2:5], v[182:185], v[236:239], v[2:5]
	s_barrier
	s_add_i32 s56, 0, 0x18000
	s_add_i32 s57, 0, 0x1c000
	v_add_u32_e32 v166, s56, v147
	v_add_u32_e32 v182, s57, v147
	ds_read_b128 v[142:145], v166
	ds_read_b128 v[158:161], v166 offset:1024
	ds_read_b128 v[162:165], v166 offset:2048
	ds_read_b128 v[166:169], v166 offset:3072
	ds_read_b128 v[170:173], v182
	ds_read_b128 v[174:177], v182 offset:1024
	ds_read_b128 v[178:181], v182 offset:2048
	ds_read_b128 v[182:185], v182 offset:3072
	s_add_u32 s34, s34, 0x40000
	s_addc_u32 s35, s35, 0
	s_mov_b32 m0, s43
	v_lshl_add_u64 v[244:245], s[34:35], 0, v[130:131]
	ds_read_b128 v[186:189], v157 offset:32768
	ds_read_b128 v[190:193], v157 offset:33792
	ds_read_b128 v[194:197], v157 offset:34816
	ds_read_b128 v[198:201], v157 offset:35840
	ds_read_b128 v[202:205], v157 offset:36864
	ds_read_b128 v[206:209], v157 offset:37888
	ds_read_b128 v[220:223], v157 offset:38912
	ds_read_b128 v[236:239], v157 offset:39936
	global_load_lds_dwordx4 v[244:245], off
	s_mov_b32 m0, s46
	v_lshl_add_u64 v[244:245], s[34:35], 0, v[134:135]
	global_load_lds_dwordx4 v[244:245], off
	s_branch .Lpadj_0
	s_nop 0
	s_nop 0
	s_nop 0
	s_nop 0
	s_nop 0
	s_nop 0
	s_nop 0
	s_nop 0

.LBB0_362:
	s_ashr_i32 s23, s22, 31
	s_lshl_b64 s[24:25], s[22:23], 19
	s_add_u32 s24, s80, s24
	s_addc_u32 s25, s81, s25
	s_and_b64 s[26:27], s[6:7], exec
	s_cselect_b32 s23, s25, s35
	s_cselect_b32 s39, s24, s34
	s_ashr_i32 s21, s20, 31
	s_lshl_b64 s[26:27], s[20:21], 19
	s_add_u32 s26, s45, s26
	s_addc_u32 s27, s46, s27
	s_and_b64 s[36:37], s[6:7], exec
	s_cselect_b32 s21, s27, s31
	s_cselect_b32 s40, s26, s30
	s_add_u32 s41, s30, 0x100
	s_addc_u32 s43, s31, 0
	s_add_u32 s30, s34, 0x40080
	s_addc_u32 s31, s35, 0
	s_mov_b32 s56, -2
	s_add_u32 s34, s30, 0xfffc0080
	s_addc_u32 s35, s31, -1
	s_add_i32 s57, 0, 0x10000
	s_cmp_eq_u32 s56, 12
	s_cselect_b32 s37, s23, s35
	s_cselect_b32 s36, s39, s34
	v_add_u32_e32 v146, s57, v155
	s_cselect_b32 s35, s21, s43
	s_cselect_b32 s34, s40, s41
	s_add_i32 s60, 0, 0x14000
	ds_read_b128 v[142:145], v146
	ds_read_b128 v[168:171], v146 offset:1024
	ds_read_b128 v[172:175], v146 offset:2048
	ds_read_b128 v[176:179], v146 offset:3072
	v_add_u32_e32 v146, s60, v155
	ds_read_b128 v[180:183], v146
	ds_read_b128 v[184:187], v146 offset:1024
	ds_read_b128 v[188:191], v146 offset:2048
	ds_read_b128 v[192:195], v146 offset:3072
	v_lshl_add_u64 v[146:147], s[30:31], 0, v[140:141]
	s_add_i32 m0, s48, 0xc000
	ds_read_b128 v[196:199], v157
	ds_read_b128 v[200:203], v157 offset:1024
	ds_read_b128 v[204:207], v157 offset:2048
	ds_read_b128 v[220:223], v157 offset:3072
	ds_read_b128 v[236:239], v157 offset:4096
	ds_read_b128 v[240:243], v157 offset:5120
	ds_read_b128 v[244:247], v157 offset:6144
	ds_read_b128 v[248:251], v157 offset:7168
	global_load_lds_dwordx4 v[146:147], off
	s_add_i32 m0, s48, 0xe000
	v_lshl_add_u64 v[146:147], s[30:31], 0, v[138:139]
	global_load_lds_dwordx4 v[146:147], off
	s_nop 0
	s_nop 0
	s_nop 0
	s_nop 0
	s_nop 0
	s_nop 0
	s_nop 0
	s_nop 0
	s_nop 0
	s_nop 0
	s_nop 0
	s_nop 0
	s_nop 0
	s_nop 0
	s_nop 0
	s_nop 0
	s_nop 0
	s_nop 0
	s_nop 0
	s_nop 0
	s_cmp_eq_u32 s38, 0
	s_cbranch_scc1 .Lsw_fw0
	s_waitcnt vmcnt(16)
	s_branch .Lsw_fj0

.Lsw_fj0:
	s_waitcnt lgkmcnt(0)
	s_barrier
	v_mfma_f32_16x16x32_bf16 v[126:129], v[142:145], v[196:199], 0
	v_mfma_f32_16x16x32_bf16 v[118:121], v[172:175], v[196:199], 0
	v_mfma_f32_16x16x32_bf16 v[110:113], v[142:145], v[204:207], 0
	v_mfma_f32_16x16x32_bf16 v[102:105], v[172:175], v[204:207], 0
	v_mfma_f32_16x16x32_bf16 v[94:97], v[142:145], v[236:239], 0
	v_mfma_f32_16x16x32_bf16 v[86:89], v[172:175], v[236:239], 0
	v_mfma_f32_16x16x32_bf16 v[78:81], v[142:145], v[244:247], 0
	v_mfma_f32_16x16x32_bf16 v[70:73], v[172:175], v[244:247], 0
	v_mfma_f32_16x16x32_bf16 v[126:129], v[168:171], v[200:203], v[126:129]
	v_mfma_f32_16x16x32_bf16 v[118:121], v[176:179], v[200:203], v[118:121]
	v_mfma_f32_16x16x32_bf16 v[110:113], v[168:171], v[220:223], v[110:113]
	v_mfma_f32_16x16x32_bf16 v[102:105], v[176:179], v[220:223], v[102:105]
	v_mfma_f32_16x16x32_bf16 v[94:97], v[168:171], v[240:243], v[94:97]
	v_mfma_f32_16x16x32_bf16 v[86:89], v[176:179], v[240:243], v[86:89]
	v_mfma_f32_16x16x32_bf16 v[78:81], v[168:171], v[248:251], v[78:81]
	v_mfma_f32_16x16x32_bf16 v[70:73], v[176:179], v[248:251], v[70:73]
	v_mfma_f32_16x16x32_bf16 v[122:125], v[180:183], v[196:199], 0
	v_mfma_f32_16x16x32_bf16 v[114:117], v[188:191], v[196:199], 0
	v_mfma_f32_16x16x32_bf16 v[106:109], v[180:183], v[204:207], 0
	v_mfma_f32_16x16x32_bf16 v[98:101], v[188:191], v[204:207], 0
	v_mfma_f32_16x16x32_bf16 v[90:93], v[180:183], v[236:239], 0
	v_mfma_f32_16x16x32_bf16 v[82:85], v[188:191], v[236:239], 0
	v_mfma_f32_16x16x32_bf16 v[74:77], v[180:183], v[244:247], 0
	v_mfma_f32_16x16x32_bf16 v[66:69], v[188:191], v[244:247], 0
	v_mfma_f32_16x16x32_bf16 v[122:125], v[184:187], v[200:203], v[122:125]
	v_mfma_f32_16x16x32_bf16 v[114:117], v[192:195], v[200:203], v[114:117]
	v_mfma_f32_16x16x32_bf16 v[106:109], v[184:187], v[220:223], v[106:109]
	v_mfma_f32_16x16x32_bf16 v[98:101], v[192:195], v[220:223], v[98:101]
	v_mfma_f32_16x16x32_bf16 v[90:93], v[184:187], v[240:243], v[90:93]
	v_mfma_f32_16x16x32_bf16 v[82:85], v[192:195], v[240:243], v[82:85]
	v_mfma_f32_16x16x32_bf16 v[74:77], v[184:187], v[248:251], v[74:77]
	v_mfma_f32_16x16x32_bf16 v[66:69], v[192:195], v[248:251], v[66:69]
	s_barrier
	s_add_i32 s57, s57, s44
	v_lshl_add_u64 v[146:147], s[34:35], 0, v[134:135]
	s_mov_b32 m0, s57
	ds_read_b128 v[196:199], v157 offset:16384
	ds_read_b128 v[200:203], v157 offset:17408
	ds_read_b128 v[204:207], v157 offset:18432
	ds_read_b128 v[220:223], v157 offset:19456
	ds_read_b128 v[236:239], v157 offset:20480
	ds_read_b128 v[240:243], v157 offset:21504
	ds_read_b128 v[244:247], v157 offset:22528
	ds_read_b128 v[248:251], v157 offset:23552
	global_load_lds_dwordx4 v[146:147], off
	s_add_i32 m0, s57, 0x2000
	s_add_u32 s58, s34, 0x40000
	v_lshl_add_u64 v[208:209], s[34:35], 0, v[130:131]
	s_addc_u32 s59, s35, 0
	s_add_i32 s57, s60, s44
	global_load_lds_dwordx4 v[208:209], off
	v_lshl_add_u64 v[224:225], s[58:59], 0, v[134:135]
	s_mov_b32 m0, s57
	v_lshl_add_u64 v[230:231], s[36:37], 0, v[132:133]
	global_load_lds_dwordx4 v[224:225], off
	s_add_i32 m0, s57, 0x2000
	v_lshl_add_u64 v[224:225], s[58:59], 0, v[130:131]
	global_load_lds_dwordx4 v[224:225], off
	s_mov_b32 m0, s48
	v_lshl_add_u64 v[224:225], s[36:37], 0, v[136:137]
	global_load_lds_dwordx4 v[224:225], off
	s_mov_b32 m0, s49
	s_nop 0
	global_load_lds_dwordx4 v[230:231], off
	s_nop 0
	s_nop 0
	s_nop 0
	s_nop 0
	s_nop 0
	s_nop 0
	s_nop 0
	s_nop 0
	s_nop 0
	s_nop 0
	s_nop 0
	s_nop 0
	s_nop 0
	s_nop 0
	s_nop 0
	s_nop 0
	s_nop 0
	s_nop 0
	s_cmp_eq_u32 s38, 0
	s_cbranch_scc1 .Lsw_fw1
	s_waitcnt vmcnt(16)
	s_branch .Lsw_fj1

.Lsw_fj1:
	s_waitcnt lgkmcnt(0)
	s_barrier
	v_mfma_f32_16x16x32_bf16 v[62:65], v[142:145], v[196:199], 0
	v_mfma_f32_16x16x32_bf16 v[54:57], v[172:175], v[196:199], 0
	v_mfma_f32_16x16x32_bf16 v[46:49], v[142:145], v[204:207], 0
	v_mfma_f32_16x16x32_bf16 v[38:41], v[172:175], v[204:207], 0
	v_mfma_f32_16x16x32_bf16 v[30:33], v[142:145], v[236:239], 0
	v_mfma_f32_16x16x32_bf16 v[22:25], v[172:175], v[236:239], 0
	v_mfma_f32_16x16x32_bf16 v[14:17], v[142:145], v[244:247], 0
	v_mfma_f32_16x16x32_bf16 v[6:9], v[172:175], v[244:247], 0
	v_mfma_f32_16x16x32_bf16 v[62:65], v[168:171], v[200:203], v[62:65]
	v_mfma_f32_16x16x32_bf16 v[54:57], v[176:179], v[200:203], v[54:57]
	v_mfma_f32_16x16x32_bf16 v[46:49], v[168:171], v[220:223], v[46:49]
	v_mfma_f32_16x16x32_bf16 v[38:41], v[176:179], v[220:223], v[38:41]
	v_mfma_f32_16x16x32_bf16 v[30:33], v[168:171], v[240:243], v[30:33]
	v_mfma_f32_16x16x32_bf16 v[22:25], v[176:179], v[240:243], v[22:25]
	v_mfma_f32_16x16x32_bf16 v[14:17], v[168:171], v[248:251], v[14:17]
	v_mfma_f32_16x16x32_bf16 v[6:9], v[176:179], v[248:251], v[6:9]
	v_mfma_f32_16x16x32_bf16 v[58:61], v[180:183], v[196:199], 0
	v_mfma_f32_16x16x32_bf16 v[50:53], v[188:191], v[196:199], 0
	v_mfma_f32_16x16x32_bf16 v[42:45], v[180:183], v[204:207], 0
	v_mfma_f32_16x16x32_bf16 v[34:37], v[188:191], v[204:207], 0
	v_mfma_f32_16x16x32_bf16 v[26:29], v[180:183], v[236:239], 0
	v_mfma_f32_16x16x32_bf16 v[18:21], v[188:191], v[236:239], 0
	v_mfma_f32_16x16x32_bf16 v[10:13], v[180:183], v[244:247], 0
	v_mfma_f32_16x16x32_bf16 v[2:5], v[188:191], v[244:247], 0
	v_mfma_f32_16x16x32_bf16 v[58:61], v[184:187], v[200:203], v[58:61]
	v_mfma_f32_16x16x32_bf16 v[50:53], v[192:195], v[200:203], v[50:53]
	v_mfma_f32_16x16x32_bf16 v[42:45], v[184:187], v[220:223], v[42:45]
	v_mfma_f32_16x16x32_bf16 v[34:37], v[192:195], v[220:223], v[34:37]
	v_mfma_f32_16x16x32_bf16 v[26:29], v[184:187], v[240:243], v[26:29]
	v_mfma_f32_16x16x32_bf16 v[18:21], v[192:195], v[240:243], v[18:21]
	v_mfma_f32_16x16x32_bf16 v[10:13], v[184:187], v[248:251], v[10:13]
	v_mfma_f32_16x16x32_bf16 v[2:5], v[192:195], v[248:251], v[2:5]
	s_barrier
	s_add_i32 s57, 0, 0x18000
	v_add_u32_e32 v164, s57, v155
	s_add_i32 s58, 0, 0x1c000
	ds_read_b128 v[142:145], v164
	ds_read_b128 v[168:171], v164 offset:1024
	ds_read_b128 v[172:175], v164 offset:2048
	ds_read_b128 v[176:179], v164 offset:3072
	v_add_u32_e32 v164, s58, v155
	ds_read_b128 v[180:183], v164
	ds_read_b128 v[184:187], v164 offset:1024
	ds_read_b128 v[188:191], v164 offset:2048
	ds_read_b128 v[192:195], v164 offset:3072
	s_add_u32 s36, s36, 0x40000
	s_addc_u32 s37, s37, 0
	s_mov_b32 m0, s50
	v_lshl_add_u64 v[252:253], s[36:37], 0, v[136:137]
	ds_read_b128 v[196:199], v157 offset:32768
	ds_read_b128 v[200:203], v157 offset:33792
	ds_read_b128 v[204:207], v157 offset:34816
	ds_read_b128 v[220:223], v157 offset:35840
	ds_read_b128 v[236:239], v157 offset:36864
	ds_read_b128 v[240:243], v157 offset:37888
	ds_read_b128 v[244:247], v157 offset:38912
	ds_read_b128 v[248:251], v157 offset:39936
	global_load_lds_dwordx4 v[252:253], off
	s_mov_b32 m0, s51
	v_lshl_add_u64 v[252:253], s[36:37], 0, v[132:133]
	global_load_lds_dwordx4 v[252:253], off
	s_branch .Lpadj_6
	s_nop 0
	s_nop 0
	s_nop 0
	s_nop 0
	s_nop 0
	s_nop 0
	s_nop 0
	s_nop 0

.LBB0_639:
	s_ashr_i32 s13, s12, 31
	s_lshl_b64 s[14:15], s[12:13], 19
	s_add_u32 s14, s80, s14
	s_addc_u32 s15, s81, s15
	s_and_b64 s[16:17], s[4:5], exec
	s_cselect_b32 s13, s15, s23
	s_cselect_b32 s19, s14, s22
	s_ashr_i32 s11, s10, 31
	s_lshl_b64 s[16:17], s[10:11], 19
	s_add_u32 s16, s26, s16
	s_addc_u32 s17, s27, s17
	s_and_b64 s[24:25], s[4:5], exec
	s_cselect_b32 s11, s17, s21
	s_cselect_b32 s41, s16, s20
	s_add_u32 s43, s20, 0x100
	s_addc_u32 s44, s21, 0
	s_add_u32 s20, s22, 0x40080
	s_addc_u32 s21, s23, 0
	s_mov_b32 s45, -2
	s_add_u32 s22, s20, 0xfffc0080
	s_addc_u32 s23, s21, -1
	s_add_i32 s46, 0, 0x10000
	s_cmp_eq_u32 s45, 12
	s_cselect_b32 s25, s13, s23
	s_cselect_b32 s24, s19, s22
	v_add_u32_e32 v150, s46, v159
	s_cselect_b32 s23, s11, s44
	s_cselect_b32 s22, s41, s43
	s_add_i32 s48, 0, 0x14000
	ds_read_b128 v[164:167], v150
	ds_read_b128 v[168:171], v150 offset:1024
	ds_read_b128 v[172:175], v150 offset:2048
	ds_read_b128 v[176:179], v150 offset:3072
	v_add_u32_e32 v150, s48, v159
	ds_read_b128 v[180:183], v150
	ds_read_b128 v[184:187], v150 offset:1024
	ds_read_b128 v[188:191], v150 offset:2048
	ds_read_b128 v[192:195], v150 offset:3072
	v_lshl_add_u64 v[150:151], s[20:21], 0, v[140:141]
	s_add_i32 m0, s30, 0xc000
	ds_read_b128 v[196:199], v162
	ds_read_b128 v[200:203], v162 offset:1024
	ds_read_b128 v[204:207], v162 offset:2048
	ds_read_b128 v[220:223], v162 offset:3072
	ds_read_b128 v[236:239], v162 offset:4096
	ds_read_b128 v[240:243], v162 offset:5120
	ds_read_b128 v[244:247], v162 offset:6144
	ds_read_b128 v[248:251], v162 offset:7168
	global_load_lds_dwordx4 v[150:151], off
	s_add_i32 m0, s30, 0xe000
	v_lshl_add_u64 v[150:151], s[20:21], 0, v[138:139]
	global_load_lds_dwordx4 v[150:151], off
	s_nop 0
	s_nop 0
	s_nop 0
	s_nop 0
	s_nop 0
	s_nop 0
	s_nop 0
	s_nop 0
	s_nop 0
	s_nop 0
	s_nop 0
	s_nop 0
	s_nop 0
	s_nop 0
	s_nop 0
	s_nop 0
	s_nop 0
	s_nop 0
	s_nop 0
	s_nop 0
	s_nop 0
	s_nop 0
	s_cmp_eq_u32 s39, 1
	s_cbranch_scc1 .Lci_fw0
	s_waitcnt vmcnt(16)
	s_branch .Lci_fj0

.Lci_fj0:
	s_waitcnt lgkmcnt(0)
	s_barrier
	v_mfma_f32_16x16x32_bf16 v[126:129], v[164:167], v[196:199], 0
	v_mfma_f32_16x16x32_bf16 v[122:125], v[172:175], v[196:199], 0
	v_mfma_f32_16x16x32_bf16 v[118:121], v[164:167], v[204:207], 0
	v_mfma_f32_16x16x32_bf16 v[114:117], v[172:175], v[204:207], 0
	v_mfma_f32_16x16x32_bf16 v[110:113], v[164:167], v[236:239], 0
	v_mfma_f32_16x16x32_bf16 v[106:109], v[172:175], v[236:239], 0
	v_mfma_f32_16x16x32_bf16 v[102:105], v[164:167], v[244:247], 0
	v_mfma_f32_16x16x32_bf16 v[98:101], v[172:175], v[244:247], 0
	v_mfma_f32_16x16x32_bf16 v[126:129], v[168:171], v[200:203], v[126:129]
	v_mfma_f32_16x16x32_bf16 v[122:125], v[176:179], v[200:203], v[122:125]
	v_mfma_f32_16x16x32_bf16 v[118:121], v[168:171], v[220:223], v[118:121]
	v_mfma_f32_16x16x32_bf16 v[114:117], v[176:179], v[220:223], v[114:117]
	v_mfma_f32_16x16x32_bf16 v[110:113], v[168:171], v[240:243], v[110:113]
	v_mfma_f32_16x16x32_bf16 v[106:109], v[176:179], v[240:243], v[106:109]
	v_mfma_f32_16x16x32_bf16 v[102:105], v[168:171], v[248:251], v[102:105]
	v_mfma_f32_16x16x32_bf16 v[98:101], v[176:179], v[248:251], v[98:101]
	v_mfma_f32_16x16x32_bf16 v[94:97], v[180:183], v[196:199], 0
	v_mfma_f32_16x16x32_bf16 v[90:93], v[188:191], v[196:199], 0
	v_mfma_f32_16x16x32_bf16 v[86:89], v[180:183], v[204:207], 0
	v_mfma_f32_16x16x32_bf16 v[82:85], v[188:191], v[204:207], 0
	v_mfma_f32_16x16x32_bf16 v[78:81], v[180:183], v[236:239], 0
	v_mfma_f32_16x16x32_bf16 v[74:77], v[188:191], v[236:239], 0
	v_mfma_f32_16x16x32_bf16 v[70:73], v[180:183], v[244:247], 0
	v_mfma_f32_16x16x32_bf16 v[66:69], v[188:191], v[244:247], 0
	v_mfma_f32_16x16x32_bf16 v[94:97], v[184:187], v[200:203], v[94:97]
	v_mfma_f32_16x16x32_bf16 v[90:93], v[192:195], v[200:203], v[90:93]
	v_mfma_f32_16x16x32_bf16 v[86:89], v[184:187], v[220:223], v[86:89]
	v_mfma_f32_16x16x32_bf16 v[82:85], v[192:195], v[220:223], v[82:85]
	v_mfma_f32_16x16x32_bf16 v[78:81], v[184:187], v[240:243], v[78:81]
	v_mfma_f32_16x16x32_bf16 v[74:77], v[192:195], v[240:243], v[74:77]
	v_mfma_f32_16x16x32_bf16 v[70:73], v[184:187], v[248:251], v[70:73]
	v_mfma_f32_16x16x32_bf16 v[66:69], v[192:195], v[248:251], v[66:69]
	s_barrier
	s_add_i32 s46, s46, s28
	v_lshl_add_u64 v[150:151], s[22:23], 0, v[134:135]
	s_mov_b32 m0, s46
	ds_read_b128 v[196:199], v162 offset:16384
	ds_read_b128 v[200:203], v162 offset:17408
	ds_read_b128 v[204:207], v162 offset:18432
	ds_read_b128 v[220:223], v162 offset:19456
	ds_read_b128 v[236:239], v162 offset:20480
	ds_read_b128 v[240:243], v162 offset:21504
	ds_read_b128 v[244:247], v162 offset:22528
	ds_read_b128 v[248:251], v162 offset:23552
	global_load_lds_dwordx4 v[150:151], off
	s_add_i32 m0, s46, 0x2000
	s_add_u32 s46, s22, 0x40000
	v_lshl_add_u64 v[208:209], s[22:23], 0, v[130:131]
	s_addc_u32 s47, s23, 0
	s_add_i32 s48, s48, s28
	global_load_lds_dwordx4 v[208:209], off
	v_lshl_add_u64 v[224:225], s[46:47], 0, v[134:135]
	s_mov_b32 m0, s48
	v_lshl_add_u64 v[252:253], s[24:25], 0, v[132:133]
	global_load_lds_dwordx4 v[224:225], off
	s_add_i32 m0, s48, 0x2000
	v_lshl_add_u64 v[224:225], s[46:47], 0, v[130:131]
	global_load_lds_dwordx4 v[224:225], off
	s_mov_b32 m0, s30
	v_lshl_add_u64 v[224:225], s[24:25], 0, v[136:137]
	global_load_lds_dwordx4 v[224:225], off
	s_mov_b32 m0, s31
	s_nop 0
	global_load_lds_dwordx4 v[252:253], off
	s_nop 0
	s_nop 0
	s_nop 0
	s_nop 0
	s_nop 0
	s_nop 0
	s_nop 0
	s_nop 0
	s_nop 0
	s_nop 0
	s_nop 0
	s_nop 0
	s_nop 0
	s_nop 0
	s_nop 0
	s_nop 0
	s_nop 0
	s_nop 0
	s_cmp_eq_u32 s39, 1
	s_cbranch_scc1 .Lci_fw1
	s_waitcnt vmcnt(16)
	s_branch .Lci_fj1

.Lci_fj1:
	s_waitcnt lgkmcnt(0)
	s_barrier
	v_mfma_f32_16x16x32_bf16 v[62:65], v[164:167], v[196:199], 0
	v_mfma_f32_16x16x32_bf16 v[58:61], v[172:175], v[196:199], 0
	v_mfma_f32_16x16x32_bf16 v[54:57], v[164:167], v[204:207], 0
	v_mfma_f32_16x16x32_bf16 v[50:53], v[172:175], v[204:207], 0
	v_mfma_f32_16x16x32_bf16 v[46:49], v[164:167], v[236:239], 0
	v_mfma_f32_16x16x32_bf16 v[42:45], v[172:175], v[236:239], 0
	v_mfma_f32_16x16x32_bf16 v[38:41], v[164:167], v[244:247], 0
	v_mfma_f32_16x16x32_bf16 v[34:37], v[172:175], v[244:247], 0
	v_mfma_f32_16x16x32_bf16 v[62:65], v[168:171], v[200:203], v[62:65]
	v_mfma_f32_16x16x32_bf16 v[58:61], v[176:179], v[200:203], v[58:61]
	v_mfma_f32_16x16x32_bf16 v[54:57], v[168:171], v[220:223], v[54:57]
	v_mfma_f32_16x16x32_bf16 v[50:53], v[176:179], v[220:223], v[50:53]
	v_mfma_f32_16x16x32_bf16 v[46:49], v[168:171], v[240:243], v[46:49]
	v_mfma_f32_16x16x32_bf16 v[42:45], v[176:179], v[240:243], v[42:45]
	v_mfma_f32_16x16x32_bf16 v[38:41], v[168:171], v[248:251], v[38:41]
	v_mfma_f32_16x16x32_bf16 v[34:37], v[176:179], v[248:251], v[34:37]
	v_mfma_f32_16x16x32_bf16 v[30:33], v[180:183], v[196:199], 0
	v_mfma_f32_16x16x32_bf16 v[26:29], v[188:191], v[196:199], 0
	v_mfma_f32_16x16x32_bf16 v[22:25], v[180:183], v[204:207], 0
	v_mfma_f32_16x16x32_bf16 v[18:21], v[188:191], v[204:207], 0
	v_mfma_f32_16x16x32_bf16 v[14:17], v[180:183], v[236:239], 0
	v_mfma_f32_16x16x32_bf16 v[10:13], v[188:191], v[236:239], 0
	v_mfma_f32_16x16x32_bf16 v[6:9], v[180:183], v[244:247], 0
	v_mfma_f32_16x16x32_bf16 v[2:5], v[188:191], v[244:247], 0
	v_mfma_f32_16x16x32_bf16 v[30:33], v[184:187], v[200:203], v[30:33]
	v_mfma_f32_16x16x32_bf16 v[26:29], v[192:195], v[200:203], v[26:29]
	v_mfma_f32_16x16x32_bf16 v[22:25], v[184:187], v[220:223], v[22:25]
	v_mfma_f32_16x16x32_bf16 v[18:21], v[192:195], v[220:223], v[18:21]
	v_mfma_f32_16x16x32_bf16 v[14:17], v[184:187], v[240:243], v[14:17]
	v_mfma_f32_16x16x32_bf16 v[10:13], v[192:195], v[240:243], v[10:13]
	v_mfma_f32_16x16x32_bf16 v[6:9], v[184:187], v[248:251], v[6:9]
	v_mfma_f32_16x16x32_bf16 v[2:5], v[192:195], v[248:251], v[2:5]
	s_barrier
	s_add_i32 s46, 0, 0x18000
	v_add_u32_e32 v163, s46, v159
	s_add_i32 s47, 0, 0x1c000
	ds_read_b128 v[164:167], v163
	ds_read_b128 v[168:171], v163 offset:1024
	ds_read_b128 v[172:175], v163 offset:2048
	ds_read_b128 v[176:179], v163 offset:3072
	v_add_u32_e32 v163, s47, v159
	ds_read_b128 v[180:183], v163
	ds_read_b128 v[184:187], v163 offset:1024
	ds_read_b128 v[188:191], v163 offset:2048
	ds_read_b128 v[192:195], v163 offset:3072
	s_add_u32 s24, s24, 0x40000
	s_addc_u32 s25, s25, 0
	s_mov_b32 m0, s34
	v_lshl_add_u64 v[230:231], s[24:25], 0, v[136:137]
	ds_read_b128 v[196:199], v162 offset:32768
	ds_read_b128 v[200:203], v162 offset:33792
	ds_read_b128 v[204:207], v162 offset:34816
	ds_read_b128 v[220:223], v162 offset:35840
	ds_read_b128 v[236:239], v162 offset:36864
	ds_read_b128 v[240:243], v162 offset:37888
	ds_read_b128 v[244:247], v162 offset:38912
	ds_read_b128 v[248:251], v162 offset:39936
	global_load_lds_dwordx4 v[230:231], off
	s_mov_b32 m0, s35
	v_lshl_add_u64 v[230:231], s[24:25], 0, v[132:133]
	global_load_lds_dwordx4 v[230:231], off
	s_branch .Lpadj_16
	s_nop 0
	s_nop 0
	s_nop 0
	s_nop 0
	s_nop 0
	s_nop 0
	s_nop 0
	s_nop 0
